# u-pass tail rescheduled so every DPP op keeps two wait states to all of its registers (hazard-clean); same math
# speedup vs baseline: 1.0264x; 1.0022x over previous
; __global__ void __launch_bounds__(NTHR, 2) fwd_megakernel(Args a) {
;     ...
;             for (int vs = 0; vs < 16; ++vs) {
;                 const unsigned char* Us = U8 + (size_t)vs * (16384 * 128) + sub * 16;
; #pragma unroll 1
;                 for (int k = 0; k < kn; ++k) {
;                     const size_t t = (size_t)gw + (size_t)(k0 + k) * NGW;
;                     u32x4 r[16];
; #pragma unroll
;                     for (int i = 0; i < 16; ++i) { const unsigned e = (unsigned)EL[k * 128 + 8 * i + grp]; r[i] = *(const u32x4*)(Us + e * 128u); }
;                     f32x2 f2[8];
;                     { const bf16_t* fr = F + t * D + vs * 128 + sub * 16; const u32x4 w0 = __builtin_nontemporal_load((const u32x4*)fr), w1 = __builtin_nontemporal_load((const u32x4*)(fr + 8));
; #pragma unroll
;                         for (int q = 0; q < 4; ++q) { f2[q] = (f32x2){bflo(w0[q]), bfhi(w0[q])}; f2[4 + q] = (f32x2){bflo(w1[q]), bfhi(w1[q])}; } }
;                     float accA = 0.f, accB = 0.f;
; #pragma unroll
;                     for (int i = 0; i < 16; ++i) {
;                         f32x2 a2 = {0.f, 0.f};
; #pragma unroll
;                         for (int q = 0; q < 4; ++q) { const int w = (int)r[i][q]; a2 += __builtin_amdgcn_cvt_pk_f32_fp8(w, false) * f2[2 * q]; a2 += __builtin_amdgcn_cvt_pk_f32_fp8(w, true) * f2[2 * q + 1]; }
;                         const float tot = red8(a2.x + a2.y);
;                         if (i < 8) accA = (sub == i) ? tot : accA; else accB = (sub == i - 8) ? tot : accB;
.Lup_jn_p:
.Lup_loop:
	s_waitcnt vmcnt(16)
	ds_read2_b32 v[158:159], v185 offset1:8
	ds_read2_b32 v[160:161], v185 offset0:16 offset1:24
	ds_read2_b32 v[162:163], v185 offset0:32 offset1:40
	ds_read2_b32 v[164:165], v185 offset0:48 offset1:56
	ds_read2_b32 v[166:167], v185 offset0:64 offset1:72
	ds_read2_b32 v[168:169], v185 offset0:80 offset1:88
	ds_read2_b32 v[170:171], v185 offset0:96 offset1:104
	ds_read2_b32 v[172:173], v185 offset0:112 offset1:120
	ds_read2st64_b32 v[188:189], v187 offset0:32 offset1:33
	v_lshlrev_b32_e32 v98, 16, v150
	v_and_b32_e32 v99, 0xffff0000, v150
	v_lshlrev_b32_e32 v100, 16, v151
	v_and_b32_e32 v101, 0xffff0000, v151
	v_lshlrev_b32_e32 v102, 16, v152
	v_and_b32_e32 v103, 0xffff0000, v152
	v_lshlrev_b32_e32 v104, 16, v153
	v_and_b32_e32 v105, 0xffff0000, v153
	v_lshlrev_b32_e32 v106, 16, v154
	v_and_b32_e32 v107, 0xffff0000, v154
	v_lshlrev_b32_e32 v108, 16, v155
	v_and_b32_e32 v109, 0xffff0000, v155
	v_lshlrev_b32_e32 v110, 16, v156
	v_and_b32_e32 v111, 0xffff0000, v156
	v_lshlrev_b32_e32 v112, 16, v157
	v_and_b32_e32 v113, 0xffff0000, v157
	global_load_dwordx4 v[150:153], v[96:97], off offset:-16 nt
	global_load_dwordx4 v[154:157], v[96:97], off nt
	s_waitcnt vmcnt(17)
	v_cvt_pk_f32_fp8_e32 v[116:117], v0
	v_cvt_pk_f32_fp8_sdwa v[118:119], v0 src0_sel:WORD_1
	v_pk_fma_f32 v[174:175], v[116:117], v[98:99], 0 op_sel_hi:[1,1,0]
	v_cvt_pk_f32_fp8_e32 v[120:121], v1
	v_pk_fma_f32 v[174:175], v[118:119], v[100:101], v[174:175]
	v_cvt_pk_f32_fp8_sdwa v[122:123], v1 src0_sel:WORD_1
	v_pk_fma_f32 v[174:175], v[120:121], v[102:103], v[174:175]
	v_cvt_pk_f32_fp8_e32 v[116:117], v2
	v_pk_fma_f32 v[174:175], v[122:123], v[104:105], v[174:175]
	v_cvt_pk_f32_fp8_sdwa v[118:119], v2 src0_sel:WORD_1
	v_pk_fma_f32 v[174:175], v[116:117], v[106:107], v[174:175]
	v_cvt_pk_f32_fp8_e32 v[120:121], v3
	v_pk_fma_f32 v[174:175], v[118:119], v[108:109], v[174:175]
	v_cvt_pk_f32_fp8_sdwa v[122:123], v3 src0_sel:WORD_1
	s_waitcnt lgkmcnt(0)
	v_lshl_add_u32 v182, v158, 7, v184
	v_pk_fma_f32 v[174:175], v[120:121], v[110:111], v[174:175]
	global_load_dwordx4 v[0:3], v182, s[98:99]
	v_pk_fma_f32 v[174:175], v[122:123], v[112:113], v[174:175]
	s_waitcnt vmcnt(17)
	v_cvt_pk_f32_fp8_e32 v[116:117], v4
	v_cvt_pk_f32_fp8_sdwa v[118:119], v4 src0_sel:WORD_1
	v_add_f32_e32 v192, v174, v175
	v_pk_fma_f32 v[176:177], v[116:117], v[98:99], 0 op_sel_hi:[1,1,0]
	v_cvt_pk_f32_fp8_e32 v[120:121], v5
	v_pk_fma_f32 v[176:177], v[118:119], v[100:101], v[176:177]
	v_cvt_pk_f32_fp8_sdwa v[122:123], v5 src0_sel:WORD_1
	v_pk_fma_f32 v[176:177], v[120:121], v[102:103], v[176:177]
	v_cvt_pk_f32_fp8_e32 v[116:117], v6
	v_pk_fma_f32 v[176:177], v[122:123], v[104:105], v[176:177]
	v_cvt_pk_f32_fp8_sdwa v[118:119], v6 src0_sel:WORD_1
	v_pk_fma_f32 v[176:177], v[116:117], v[106:107], v[176:177]
	v_cvt_pk_f32_fp8_e32 v[120:121], v7
	v_pk_fma_f32 v[176:177], v[118:119], v[108:109], v[176:177]
	v_cvt_pk_f32_fp8_sdwa v[122:123], v7 src0_sel:WORD_1
	v_lshl_add_u32 v183, v159, 7, v184
	v_pk_fma_f32 v[176:177], v[120:121], v[110:111], v[176:177]
	global_load_dwordx4 v[4:7], v183, s[98:99]
	v_pk_fma_f32 v[176:177], v[122:123], v[112:113], v[176:177]
	s_waitcnt vmcnt(17)
	v_cvt_pk_f32_fp8_e32 v[116:117], v8
	v_cvt_pk_f32_fp8_sdwa v[118:119], v8 src0_sel:WORD_1
	v_add_f32_e32 v193, v176, v177
	v_pk_fma_f32 v[174:175], v[116:117], v[98:99], 0 op_sel_hi:[1,1,0]
	v_cvt_pk_f32_fp8_e32 v[120:121], v9
	v_pk_fma_f32 v[174:175], v[118:119], v[100:101], v[174:175]
	v_cvt_pk_f32_fp8_sdwa v[122:123], v9 src0_sel:WORD_1
	v_pk_fma_f32 v[174:175], v[120:121], v[102:103], v[174:175]
	v_cvt_pk_f32_fp8_e32 v[116:117], v10
	v_pk_fma_f32 v[174:175], v[122:123], v[104:105], v[174:175]
	v_cvt_pk_f32_fp8_sdwa v[118:119], v10 src0_sel:WORD_1
	v_pk_fma_f32 v[174:175], v[116:117], v[106:107], v[174:175]
	v_cvt_pk_f32_fp8_e32 v[120:121], v11
	v_pk_fma_f32 v[174:175], v[118:119], v[108:109], v[174:175]
	v_cvt_pk_f32_fp8_sdwa v[122:123], v11 src0_sel:WORD_1
	v_lshl_add_u32 v182, v160, 7, v184
	v_pk_fma_f32 v[174:175], v[120:121], v[110:111], v[174:175]
	global_load_dwordx4 v[8:11], v182, s[98:99]
	v_pk_fma_f32 v[174:175], v[122:123], v[112:113], v[174:175]
	s_waitcnt vmcnt(17)
	v_cvt_pk_f32_fp8_e32 v[116:117], v12
	v_cvt_pk_f32_fp8_sdwa v[118:119], v12 src0_sel:WORD_1
	v_add_f32_e32 v194, v174, v175
	v_pk_fma_f32 v[176:177], v[116:117], v[98:99], 0 op_sel_hi:[1,1,0]
	v_cvt_pk_f32_fp8_e32 v[120:121], v13
	v_pk_fma_f32 v[176:177], v[118:119], v[100:101], v[176:177]
	v_cvt_pk_f32_fp8_sdwa v[122:123], v13 src0_sel:WORD_1
	v_pk_fma_f32 v[176:177], v[120:121], v[102:103], v[176:177]
	v_cvt_pk_f32_fp8_e32 v[116:117], v14
	v_pk_fma_f32 v[176:177], v[122:123], v[104:105], v[176:177]
	v_cvt_pk_f32_fp8_sdwa v[118:119], v14 src0_sel:WORD_1
	v_pk_fma_f32 v[176:177], v[116:117], v[106:107], v[176:177]
	v_cvt_pk_f32_fp8_e32 v[120:121], v15
	v_pk_fma_f32 v[176:177], v[118:119], v[108:109], v[176:177]
	v_cvt_pk_f32_fp8_sdwa v[122:123], v15 src0_sel:WORD_1
	v_lshl_add_u32 v183, v161, 7, v184
	v_pk_fma_f32 v[176:177], v[120:121], v[110:111], v[176:177]
	global_load_dwordx4 v[12:15], v183, s[98:99]
	v_pk_fma_f32 v[176:177], v[122:123], v[112:113], v[176:177]
	s_waitcnt vmcnt(17)
; __global__ void __launch_bounds__(NTHR, 2) fwd_megakernel(Args a) {
;     ...
; #pragma unroll
;                     for (int i = 0; i < 16; ++i) {
;                         f32x2 a2 = {0.f, 0.f};
; #pragma unroll
;                         for (int q = 0; q < 4; ++q) { const int w = (int)r[i][q]; a2 += __builtin_amdgcn_cvt_pk_f32_fp8(w, false) * f2[2 * q]; a2 += __builtin_amdgcn_cvt_pk_f32_fp8(w, true) * f2[2 * q + 1]; }
;                         const float tot = red8(a2.x + a2.y);
;                         if (i < 8) accA = (sub == i) ? tot : accA; else accB = (sub == i - 8) ? tot : accB;
	v_cvt_pk_f32_fp8_e32 v[116:117], v16
	v_cvt_pk_f32_fp8_sdwa v[118:119], v16 src0_sel:WORD_1
	v_add_f32_e32 v195, v176, v177
	v_pk_fma_f32 v[174:175], v[116:117], v[98:99], 0 op_sel_hi:[1,1,0]
	v_cvt_pk_f32_fp8_e32 v[120:121], v17
	v_pk_fma_f32 v[174:175], v[118:119], v[100:101], v[174:175]
	v_cvt_pk_f32_fp8_sdwa v[122:123], v17 src0_sel:WORD_1
	v_pk_fma_f32 v[174:175], v[120:121], v[102:103], v[174:175]
	v_cvt_pk_f32_fp8_e32 v[116:117], v18
	v_pk_fma_f32 v[174:175], v[122:123], v[104:105], v[174:175]
	v_cvt_pk_f32_fp8_sdwa v[118:119], v18 src0_sel:WORD_1
	v_pk_fma_f32 v[174:175], v[116:117], v[106:107], v[174:175]
	v_cvt_pk_f32_fp8_e32 v[120:121], v19
	v_pk_fma_f32 v[174:175], v[118:119], v[108:109], v[174:175]
	v_cvt_pk_f32_fp8_sdwa v[122:123], v19 src0_sel:WORD_1
	v_lshl_add_u32 v182, v162, 7, v184
	v_pk_fma_f32 v[174:175], v[120:121], v[110:111], v[174:175]
	global_load_dwordx4 v[16:19], v182, s[98:99]
	v_pk_fma_f32 v[174:175], v[122:123], v[112:113], v[174:175]
	s_waitcnt vmcnt(17)
	v_cvt_pk_f32_fp8_e32 v[116:117], v20
	v_cvt_pk_f32_fp8_sdwa v[118:119], v20 src0_sel:WORD_1
	v_add_f32_e32 v196, v174, v175
	v_pk_fma_f32 v[176:177], v[116:117], v[98:99], 0 op_sel_hi:[1,1,0]
	v_cvt_pk_f32_fp8_e32 v[120:121], v21
	v_pk_fma_f32 v[176:177], v[118:119], v[100:101], v[176:177]
	v_cvt_pk_f32_fp8_sdwa v[122:123], v21 src0_sel:WORD_1
	v_pk_fma_f32 v[176:177], v[120:121], v[102:103], v[176:177]
	v_cvt_pk_f32_fp8_e32 v[116:117], v22
	v_pk_fma_f32 v[176:177], v[122:123], v[104:105], v[176:177]
	v_cvt_pk_f32_fp8_sdwa v[118:119], v22 src0_sel:WORD_1
	v_pk_fma_f32 v[176:177], v[116:117], v[106:107], v[176:177]
	v_cvt_pk_f32_fp8_e32 v[120:121], v23
	v_pk_fma_f32 v[176:177], v[118:119], v[108:109], v[176:177]
	v_cvt_pk_f32_fp8_sdwa v[122:123], v23 src0_sel:WORD_1
	v_lshl_add_u32 v183, v163, 7, v184
	v_pk_fma_f32 v[176:177], v[120:121], v[110:111], v[176:177]
	global_load_dwordx4 v[20:23], v183, s[98:99]
	v_pk_fma_f32 v[176:177], v[122:123], v[112:113], v[176:177]
	s_waitcnt vmcnt(17)
	v_cvt_pk_f32_fp8_e32 v[116:117], v24
	v_cvt_pk_f32_fp8_sdwa v[118:119], v24 src0_sel:WORD_1
	v_add_f32_e32 v197, v176, v177
	v_pk_fma_f32 v[174:175], v[116:117], v[98:99], 0 op_sel_hi:[1,1,0]
	v_cvt_pk_f32_fp8_e32 v[120:121], v25
	v_pk_fma_f32 v[174:175], v[118:119], v[100:101], v[174:175]
	v_cvt_pk_f32_fp8_sdwa v[122:123], v25 src0_sel:WORD_1
	v_pk_fma_f32 v[174:175], v[120:121], v[102:103], v[174:175]
	v_cvt_pk_f32_fp8_e32 v[116:117], v26
	v_pk_fma_f32 v[174:175], v[122:123], v[104:105], v[174:175]
	v_cvt_pk_f32_fp8_sdwa v[118:119], v26 src0_sel:WORD_1
	v_pk_fma_f32 v[174:175], v[116:117], v[106:107], v[174:175]
	v_cvt_pk_f32_fp8_e32 v[120:121], v27
	v_pk_fma_f32 v[174:175], v[118:119], v[108:109], v[174:175]
	v_cvt_pk_f32_fp8_sdwa v[122:123], v27 src0_sel:WORD_1
	v_lshl_add_u32 v182, v164, 7, v184
	v_pk_fma_f32 v[174:175], v[120:121], v[110:111], v[174:175]
	global_load_dwordx4 v[24:27], v182, s[98:99]
	v_pk_fma_f32 v[174:175], v[122:123], v[112:113], v[174:175]
	s_waitcnt vmcnt(17)
	v_cvt_pk_f32_fp8_e32 v[116:117], v28
	v_cvt_pk_f32_fp8_sdwa v[118:119], v28 src0_sel:WORD_1
	v_add_f32_e32 v198, v174, v175
	v_pk_fma_f32 v[176:177], v[116:117], v[98:99], 0 op_sel_hi:[1,1,0]
	v_cvt_pk_f32_fp8_e32 v[120:121], v29
	v_pk_fma_f32 v[176:177], v[118:119], v[100:101], v[176:177]
	v_cvt_pk_f32_fp8_sdwa v[122:123], v29 src0_sel:WORD_1
	v_pk_fma_f32 v[176:177], v[120:121], v[102:103], v[176:177]
	v_cvt_pk_f32_fp8_e32 v[116:117], v30
	v_pk_fma_f32 v[176:177], v[122:123], v[104:105], v[176:177]
	v_cvt_pk_f32_fp8_sdwa v[118:119], v30 src0_sel:WORD_1
	v_pk_fma_f32 v[176:177], v[116:117], v[106:107], v[176:177]
	v_cvt_pk_f32_fp8_e32 v[120:121], v31
	v_pk_fma_f32 v[176:177], v[118:119], v[108:109], v[176:177]
	v_cvt_pk_f32_fp8_sdwa v[122:123], v31 src0_sel:WORD_1
	v_lshl_add_u32 v183, v165, 7, v184
	v_pk_fma_f32 v[176:177], v[120:121], v[110:111], v[176:177]
	global_load_dwordx4 v[28:31], v183, s[98:99]
	v_pk_fma_f32 v[176:177], v[122:123], v[112:113], v[176:177]
	s_waitcnt vmcnt(17)
	v_cvt_pk_f32_fp8_e32 v[116:117], v32
	v_cvt_pk_f32_fp8_sdwa v[118:119], v32 src0_sel:WORD_1
	v_add_f32_e32 v199, v176, v177
	v_pk_fma_f32 v[174:175], v[116:117], v[98:99], 0 op_sel_hi:[1,1,0]
	v_cvt_pk_f32_fp8_e32 v[120:121], v33
	v_pk_fma_f32 v[174:175], v[118:119], v[100:101], v[174:175]
	v_add_f32_dpp v192, v192, v192 row_shl:4 row_mask:0xf bank_mask:0x5
	v_cvt_pk_f32_fp8_sdwa v[122:123], v33 src0_sel:WORD_1
	v_pk_fma_f32 v[174:175], v[120:121], v[102:103], v[174:175]
	v_cvt_pk_f32_fp8_e32 v[116:117], v34
	v_pk_fma_f32 v[174:175], v[122:123], v[104:105], v[174:175]
	v_add_f32_dpp v192, v196, v196 row_shr:4 row_mask:0xf bank_mask:0xa
	v_cvt_pk_f32_fp8_sdwa v[118:119], v34 src0_sel:WORD_1
	v_pk_fma_f32 v[174:175], v[116:117], v[106:107], v[174:175]
	v_cvt_pk_f32_fp8_e32 v[120:121], v35
	v_pk_fma_f32 v[174:175], v[118:119], v[108:109], v[174:175]
	v_add_f32_dpp v193, v193, v193 row_shl:4 row_mask:0xf bank_mask:0x5
	v_cvt_pk_f32_fp8_sdwa v[122:123], v35 src0_sel:WORD_1
	v_lshl_add_u32 v182, v166, 7, v184
	v_pk_fma_f32 v[174:175], v[120:121], v[110:111], v[174:175]
	global_load_dwordx4 v[32:35], v182, s[98:99]
	v_add_f32_dpp v193, v197, v197 row_shr:4 row_mask:0xf bank_mask:0xa
	v_pk_fma_f32 v[174:175], v[122:123], v[112:113], v[174:175]
	s_waitcnt vmcnt(17)
; __global__ void __launch_bounds__(NTHR, 2) fwd_megakernel(Args a) {
;     ...
;                     for (int i = 0; i < 16; ++i) { const unsigned e = (unsigned)EL[k * 128 + 8 * i + grp]; r[i] = *(const u32x4*)(Us + e * 128u); }
;                     f32x2 f2[8];
;                     { const bf16_t* fr = F + t * D + vs * 128 + sub * 16; const u32x4 w0 = __builtin_nontemporal_load((const u32x4*)fr), w1 = __builtin_nontemporal_load((const u32x4*)(fr + 8));
; #pragma unroll
;                         for (int q = 0; q < 4; ++q) { f2[q] = (f32x2){bflo(w0[q]), bfhi(w0[q])}; f2[4 + q] = (f32x2){bflo(w1[q]), bfhi(w1[q])}; } }
;                     float accA = 0.f, accB = 0.f;
; #pragma unroll
;                     for (int i = 0; i < 16; ++i) {
;                         f32x2 a2 = {0.f, 0.f};
; #pragma unroll
;                         for (int q = 0; q < 4; ++q) { const int w = (int)r[i][q]; a2 += __builtin_amdgcn_cvt_pk_f32_fp8(w, false) * f2[2 * q]; a2 += __builtin_amdgcn_cvt_pk_f32_fp8(w, true) * f2[2 * q + 1]; }
;                         const float tot = red8(a2.x + a2.y);
;                         if (i < 8) accA = (sub == i) ? tot : accA; else accB = (sub == i - 8) ? tot : accB;
	v_cvt_pk_f32_fp8_e32 v[116:117], v36
	v_cvt_pk_f32_fp8_sdwa v[118:119], v36 src0_sel:WORD_1
	v_add_f32_e32 v200, v174, v175
	v_pk_fma_f32 v[176:177], v[116:117], v[98:99], 0 op_sel_hi:[1,1,0]
	v_cvt_pk_f32_fp8_e32 v[120:121], v37
	v_pk_fma_f32 v[176:177], v[118:119], v[100:101], v[176:177]
	v_add_f32_dpp v194, v194, v194 row_shl:4 row_mask:0xf bank_mask:0x5
	v_cvt_pk_f32_fp8_sdwa v[122:123], v37 src0_sel:WORD_1
	v_pk_fma_f32 v[176:177], v[120:121], v[102:103], v[176:177]
	v_cvt_pk_f32_fp8_e32 v[116:117], v38
	v_pk_fma_f32 v[176:177], v[122:123], v[104:105], v[176:177]
	v_add_f32_dpp v194, v198, v198 row_shr:4 row_mask:0xf bank_mask:0xa
	v_cvt_pk_f32_fp8_sdwa v[118:119], v38 src0_sel:WORD_1
	v_pk_fma_f32 v[176:177], v[116:117], v[106:107], v[176:177]
	v_cvt_pk_f32_fp8_e32 v[120:121], v39
	v_pk_fma_f32 v[176:177], v[118:119], v[108:109], v[176:177]
	v_add_f32_dpp v195, v195, v195 row_shl:4 row_mask:0xf bank_mask:0x5
	v_cvt_pk_f32_fp8_sdwa v[122:123], v39 src0_sel:WORD_1
	v_lshl_add_u32 v183, v167, 7, v184
	v_pk_fma_f32 v[176:177], v[120:121], v[110:111], v[176:177]
	global_load_dwordx4 v[36:39], v183, s[98:99]
	v_add_f32_dpp v195, v199, v199 row_shr:4 row_mask:0xf bank_mask:0xa
	v_pk_fma_f32 v[176:177], v[122:123], v[112:113], v[176:177]
	s_waitcnt vmcnt(17)
	v_cvt_pk_f32_fp8_e32 v[116:117], v40
	v_cvt_pk_f32_fp8_sdwa v[118:119], v40 src0_sel:WORD_1
	v_add_f32_e32 v201, v176, v177
	v_pk_fma_f32 v[174:175], v[116:117], v[98:99], 0 op_sel_hi:[1,1,0]
	v_cvt_pk_f32_fp8_e32 v[120:121], v41
	v_pk_fma_f32 v[174:175], v[118:119], v[100:101], v[174:175]
	v_cndmask_b32_e64 v208, v192, v194, s[12:13]
	v_cvt_pk_f32_fp8_sdwa v[122:123], v41 src0_sel:WORD_1
	v_pk_fma_f32 v[174:175], v[120:121], v[102:103], v[174:175]
	v_cvt_pk_f32_fp8_e32 v[116:117], v42
	v_pk_fma_f32 v[174:175], v[122:123], v[104:105], v[174:175]
	v_cndmask_b32_e64 v209, v194, v192, s[12:13]
	v_cvt_pk_f32_fp8_sdwa v[118:119], v42 src0_sel:WORD_1
	v_pk_fma_f32 v[174:175], v[116:117], v[106:107], v[174:175]
	v_cvt_pk_f32_fp8_e32 v[120:121], v43
	v_pk_fma_f32 v[174:175], v[118:119], v[108:109], v[174:175]
	v_cndmask_b32_e64 v211, v195, v193, s[12:13]
	v_cvt_pk_f32_fp8_sdwa v[122:123], v43 src0_sel:WORD_1
	v_lshl_add_u32 v182, v168, 7, v184
	v_pk_fma_f32 v[174:175], v[120:121], v[110:111], v[174:175]
	global_load_dwordx4 v[40:43], v182, s[98:99]
	v_cndmask_b32_e64 v210, v193, v195, s[12:13]
	v_pk_fma_f32 v[174:175], v[122:123], v[112:113], v[174:175]
	s_waitcnt vmcnt(17)
	v_cvt_pk_f32_fp8_e32 v[116:117], v44
	v_cvt_pk_f32_fp8_sdwa v[118:119], v44 src0_sel:WORD_1
	v_add_f32_e32 v202, v174, v175
	v_pk_fma_f32 v[176:177], v[116:117], v[98:99], 0 op_sel_hi:[1,1,0]
	v_cvt_pk_f32_fp8_e32 v[120:121], v45
	v_pk_fma_f32 v[176:177], v[118:119], v[100:101], v[176:177]
	v_add_f32_dpp v208, v209, v208 quad_perm:[2,3,0,1] row_mask:0xf bank_mask:0xf
	v_cvt_pk_f32_fp8_sdwa v[122:123], v45 src0_sel:WORD_1
	v_pk_fma_f32 v[176:177], v[120:121], v[102:103], v[176:177]
	v_cvt_pk_f32_fp8_e32 v[116:117], v46
	v_pk_fma_f32 v[176:177], v[122:123], v[104:105], v[176:177]
	v_add_f32_dpp v210, v211, v210 quad_perm:[2,3,0,1] row_mask:0xf bank_mask:0xf
	v_cvt_pk_f32_fp8_sdwa v[118:119], v46 src0_sel:WORD_1
	v_pk_fma_f32 v[176:177], v[116:117], v[106:107], v[176:177]
	v_cvt_pk_f32_fp8_e32 v[120:121], v47
	v_pk_fma_f32 v[176:177], v[118:119], v[108:109], v[176:177]
	v_cndmask_b32_e64 v209, v210, v208, s[14:15]
	v_cvt_pk_f32_fp8_sdwa v[122:123], v47 src0_sel:WORD_1
	v_lshl_add_u32 v183, v169, 7, v184
	v_pk_fma_f32 v[176:177], v[120:121], v[110:111], v[176:177]
	global_load_dwordx4 v[44:47], v183, s[98:99]
	v_cndmask_b32_e64 v211, v208, v210, s[14:15]
	v_pk_fma_f32 v[176:177], v[122:123], v[112:113], v[176:177]
	s_waitcnt vmcnt(17)
	v_cvt_pk_f32_fp8_e32 v[116:117], v48
	v_cvt_pk_f32_fp8_sdwa v[118:119], v48 src0_sel:WORD_1
	v_add_f32_e32 v203, v176, v177
	v_pk_fma_f32 v[174:175], v[116:117], v[98:99], 0 op_sel_hi:[1,1,0]
	v_cvt_pk_f32_fp8_e32 v[120:121], v49
	v_pk_fma_f32 v[174:175], v[118:119], v[100:101], v[174:175]
	v_add_f32_dpp v180, v209, v211 quad_perm:[1,0,3,2] row_mask:0xf bank_mask:0xf
	v_cvt_pk_f32_fp8_sdwa v[122:123], v49 src0_sel:WORD_1
	v_pk_fma_f32 v[174:175], v[120:121], v[102:103], v[174:175]
	v_cvt_pk_f32_fp8_e32 v[116:117], v50
	v_pk_fma_f32 v[174:175], v[122:123], v[104:105], v[174:175]
	v_cvt_pk_f32_fp8_sdwa v[118:119], v50 src0_sel:WORD_1
	v_pk_fma_f32 v[174:175], v[116:117], v[106:107], v[174:175]
	v_cvt_pk_f32_fp8_e32 v[120:121], v51
	v_pk_fma_f32 v[174:175], v[118:119], v[108:109], v[174:175]
	v_cvt_pk_f32_fp8_sdwa v[122:123], v51 src0_sel:WORD_1
	v_lshl_add_u32 v182, v170, 7, v184
	v_pk_fma_f32 v[174:175], v[120:121], v[110:111], v[174:175]
	global_load_dwordx4 v[48:51], v182, s[98:99]
	v_pk_fma_f32 v[174:175], v[122:123], v[112:113], v[174:175]
	s_waitcnt vmcnt(17)
; __global__ void __launch_bounds__(NTHR, 2) fwd_megakernel(Args a) {
;     ...
;                     for (int i = 0; i < 16; ++i) {
;                         f32x2 a2 = {0.f, 0.f};
; #pragma unroll
;                         for (int q = 0; q < 4; ++q) { const int w = (int)r[i][q]; a2 += __builtin_amdgcn_cvt_pk_f32_fp8(w, false) * f2[2 * q]; a2 += __builtin_amdgcn_cvt_pk_f32_fp8(w, true) * f2[2 * q + 1]; }
;                         const float tot = red8(a2.x + a2.y);
;                         if (i < 8) accA = (sub == i) ? tot : accA; else accB = (sub == i - 8) ? tot : accB;
;                     }
;                     HW[k * 128 + sp] += accA; HW[k * 128 + 64 + sp] += accB;
	v_cvt_pk_f32_fp8_e32 v[116:117], v52
	v_cvt_pk_f32_fp8_sdwa v[118:119], v52 src0_sel:WORD_1
	v_add_f32_e32 v204, v174, v175
	v_pk_fma_f32 v[176:177], v[116:117], v[98:99], 0 op_sel_hi:[1,1,0]
	v_cvt_pk_f32_fp8_e32 v[120:121], v53
	v_pk_fma_f32 v[176:177], v[118:119], v[100:101], v[176:177]
	v_cvt_pk_f32_fp8_sdwa v[122:123], v53 src0_sel:WORD_1
	v_pk_fma_f32 v[176:177], v[120:121], v[102:103], v[176:177]
	v_cvt_pk_f32_fp8_e32 v[116:117], v54
	v_pk_fma_f32 v[176:177], v[122:123], v[104:105], v[176:177]
	v_cvt_pk_f32_fp8_sdwa v[118:119], v54 src0_sel:WORD_1
	v_pk_fma_f32 v[176:177], v[116:117], v[106:107], v[176:177]
	v_cvt_pk_f32_fp8_e32 v[120:121], v55
	v_pk_fma_f32 v[176:177], v[118:119], v[108:109], v[176:177]
	v_cvt_pk_f32_fp8_sdwa v[122:123], v55 src0_sel:WORD_1
	v_lshl_add_u32 v183, v171, 7, v184
	v_pk_fma_f32 v[176:177], v[120:121], v[110:111], v[176:177]
	global_load_dwordx4 v[52:55], v183, s[98:99]
	v_pk_fma_f32 v[176:177], v[122:123], v[112:113], v[176:177]
	s_waitcnt vmcnt(17)
	v_cvt_pk_f32_fp8_e32 v[116:117], v56
	v_cvt_pk_f32_fp8_sdwa v[118:119], v56 src0_sel:WORD_1
	v_add_f32_e32 v205, v176, v177
	v_pk_fma_f32 v[174:175], v[116:117], v[98:99], 0 op_sel_hi:[1,1,0]
	v_cvt_pk_f32_fp8_e32 v[120:121], v57
	v_pk_fma_f32 v[174:175], v[118:119], v[100:101], v[174:175]
	v_cvt_pk_f32_fp8_sdwa v[122:123], v57 src0_sel:WORD_1
	v_pk_fma_f32 v[174:175], v[120:121], v[102:103], v[174:175]
	v_cvt_pk_f32_fp8_e32 v[116:117], v58
	v_pk_fma_f32 v[174:175], v[122:123], v[104:105], v[174:175]
	v_cvt_pk_f32_fp8_sdwa v[118:119], v58 src0_sel:WORD_1
	v_pk_fma_f32 v[174:175], v[116:117], v[106:107], v[174:175]
	v_cvt_pk_f32_fp8_e32 v[120:121], v59
	v_pk_fma_f32 v[174:175], v[118:119], v[108:109], v[174:175]
	v_cvt_pk_f32_fp8_sdwa v[122:123], v59 src0_sel:WORD_1
	v_lshl_add_u32 v182, v172, 7, v184
	v_pk_fma_f32 v[174:175], v[120:121], v[110:111], v[174:175]
	global_load_dwordx4 v[56:59], v182, s[98:99]
	v_pk_fma_f32 v[174:175], v[122:123], v[112:113], v[174:175]
	s_waitcnt vmcnt(17)
	v_cvt_pk_f32_fp8_e32 v[116:117], v60
	v_cvt_pk_f32_fp8_sdwa v[118:119], v60 src0_sel:WORD_1
	v_add_f32_e32 v206, v174, v175
	v_pk_fma_f32 v[176:177], v[116:117], v[98:99], 0 op_sel_hi:[1,1,0]
	v_cvt_pk_f32_fp8_e32 v[120:121], v61
	v_pk_fma_f32 v[176:177], v[118:119], v[100:101], v[176:177]
	v_cvt_pk_f32_fp8_sdwa v[122:123], v61 src0_sel:WORD_1
	v_pk_fma_f32 v[176:177], v[120:121], v[102:103], v[176:177]
	v_cvt_pk_f32_fp8_e32 v[116:117], v62
	v_pk_fma_f32 v[176:177], v[122:123], v[104:105], v[176:177]
	v_cvt_pk_f32_fp8_sdwa v[118:119], v62 src0_sel:WORD_1
	v_pk_fma_f32 v[176:177], v[116:117], v[106:107], v[176:177]
	v_cvt_pk_f32_fp8_e32 v[120:121], v63
	v_pk_fma_f32 v[176:177], v[118:119], v[108:109], v[176:177]
	v_cvt_pk_f32_fp8_sdwa v[122:123], v63 src0_sel:WORD_1
	v_lshl_add_u32 v183, v173, 7, v184
	v_pk_fma_f32 v[176:177], v[120:121], v[110:111], v[176:177]
	global_load_dwordx4 v[60:63], v183, s[98:99]
	v_pk_fma_f32 v[176:177], v[122:123], v[112:113], v[176:177]
	s_nop 0
	v_add_f32_e32 v207, v176, v177
	v_add_f32_dpp v200, v200, v200 row_shl:4 row_mask:0xf bank_mask:0x5
	v_add_f32_dpp v201, v201, v201 row_shl:4 row_mask:0xf bank_mask:0x5
	v_add_f32_dpp v202, v202, v202 row_shl:4 row_mask:0xf bank_mask:0x5
	v_add_f32_dpp v203, v203, v203 row_shl:4 row_mask:0xf bank_mask:0x5
	v_add_f32_dpp v200, v204, v204 row_shr:4 row_mask:0xf bank_mask:0xa
	v_add_f32_dpp v201, v205, v205 row_shr:4 row_mask:0xf bank_mask:0xa
	v_add_f32_dpp v202, v206, v206 row_shr:4 row_mask:0xf bank_mask:0xa
	v_add_f32_dpp v203, v207, v207 row_shr:4 row_mask:0xf bank_mask:0xa
	v_cndmask_b32_e64 v208, v200, v202, s[12:13]
	v_cndmask_b32_e64 v209, v202, v200, s[12:13]
	v_cndmask_b32_e64 v211, v203, v201, s[12:13]
	v_cndmask_b32_e64 v210, v201, v203, s[12:13]
	v_add_f32_e32 v188, v180, v188
	v_add_f32_dpp v208, v209, v208 quad_perm:[2,3,0,1] row_mask:0xf bank_mask:0xf
	v_add_f32_dpp v210, v211, v210 quad_perm:[2,3,0,1] row_mask:0xf bank_mask:0xf
	v_cndmask_b32_e64 v209, v210, v208, s[14:15]
	v_cndmask_b32_e64 v211, v208, v210, s[14:15]
	s_add_i32 s100, s100, -1
	s_nop 0
	v_add_f32_dpp v181, v209, v211 quad_perm:[1,0,3,2] row_mask:0xf bank_mask:0xf
	s_nop 0
	v_add_f32_e32 v189, v181, v189
	ds_write2st64_b32 v187, v188, v189 offset0:32 offset1:33
	v_add_u32_e32 v187, v185, v82
	s_add_i32 s101, s101, 1
	s_cmp_lt_u32 s101, s33
	s_cbranch_scc1 .Lup_nw_l
	s_mov_b32 s101, 0
	s_add_u32 s98, s98, 0x200000
	s_addc_u32 s99, s99, 0
	v_lshl_add_u64 v[92:93], v[92:93], 0, s[78:79]
	v_mov_b32_e32 v185, v124
	v_mov_b64_e32 v[96:97], v[92:93]
	s_branch .Lup_jn_l
